# phase0 modulation GEMV: 16 weight-row loads per block issued up front with counted waits (were load->vmcnt(0)->fma one at a time)
# speedup vs baseline: 1.0629x; 1.0056x over previous
.LBB0_141:
	v_lshl_add_u64 v[50:51], v[48:49], 0, s[16:17]
	v_mov_b32_e32 v224, v50
	v_mov_b32_e32 v225, v51
	global_load_dwordx4 v[160:163], v[224:225], off nt
	v_add_co_u32_e32 v224, vcc, 0x3000, v224
	s_nop 1
	v_addc_co_u32_e32 v225, vcc, 0, v225, vcc
	global_load_dwordx4 v[164:167], v[224:225], off nt
	v_add_co_u32_e32 v224, vcc, 0x3000, v224
	s_nop 1
	v_addc_co_u32_e32 v225, vcc, 0, v225, vcc
	global_load_dwordx4 v[168:171], v[224:225], off nt
	v_add_co_u32_e32 v224, vcc, 0x3000, v224
	s_nop 1
	v_addc_co_u32_e32 v225, vcc, 0, v225, vcc
	global_load_dwordx4 v[172:175], v[224:225], off nt
	v_add_co_u32_e32 v224, vcc, 0x3000, v224
	s_nop 1
	v_addc_co_u32_e32 v225, vcc, 0, v225, vcc
	global_load_dwordx4 v[176:179], v[224:225], off nt
	v_add_co_u32_e32 v224, vcc, 0x3000, v224
	s_nop 1
	v_addc_co_u32_e32 v225, vcc, 0, v225, vcc
	global_load_dwordx4 v[180:183], v[224:225], off nt
	v_add_co_u32_e32 v224, vcc, 0x3000, v224
	s_nop 1
	v_addc_co_u32_e32 v225, vcc, 0, v225, vcc
	global_load_dwordx4 v[184:187], v[224:225], off nt
	v_add_co_u32_e32 v224, vcc, 0x3000, v224
	s_nop 1
	v_addc_co_u32_e32 v225, vcc, 0, v225, vcc
	global_load_dwordx4 v[188:191], v[224:225], off nt
	v_add_co_u32_e32 v224, vcc, 0x3000, v224
	s_nop 1
	v_addc_co_u32_e32 v225, vcc, 0, v225, vcc
	global_load_dwordx4 v[192:195], v[224:225], off nt
	v_add_co_u32_e32 v224, vcc, 0x3000, v224
	s_nop 1
	v_addc_co_u32_e32 v225, vcc, 0, v225, vcc
	global_load_dwordx4 v[196:199], v[224:225], off nt
	v_add_co_u32_e32 v224, vcc, 0x3000, v224
	s_nop 1
	v_addc_co_u32_e32 v225, vcc, 0, v225, vcc
	global_load_dwordx4 v[200:203], v[224:225], off nt
	v_add_co_u32_e32 v224, vcc, 0x3000, v224
	s_nop 1
	v_addc_co_u32_e32 v225, vcc, 0, v225, vcc
	global_load_dwordx4 v[204:207], v[224:225], off nt
	v_add_co_u32_e32 v224, vcc, 0x3000, v224
	s_nop 1
	v_addc_co_u32_e32 v225, vcc, 0, v225, vcc
	global_load_dwordx4 v[208:211], v[224:225], off nt
	v_add_co_u32_e32 v224, vcc, 0x3000, v224
	s_nop 1
	v_addc_co_u32_e32 v225, vcc, 0, v225, vcc
	global_load_dwordx4 v[212:215], v[224:225], off nt
	v_add_co_u32_e32 v224, vcc, 0x3000, v224
	s_nop 1
	v_addc_co_u32_e32 v225, vcc, 0, v225, vcc
	global_load_dwordx4 v[216:219], v[224:225], off nt
	v_add_co_u32_e32 v224, vcc, 0x3000, v224
	s_nop 1
	v_addc_co_u32_e32 v225, vcc, 0, v225, vcc
	global_load_dwordx4 v[220:223], v[224:225], off nt
	ds_read_b128 v[80:83], v32
	ds_read_b128 v[28:31], v32 offset:16
	ds_read_b128 v[24:27], v32 offset:32
	ds_read_b128 v[20:23], v32 offset:48
	s_movk_i32 s0, 0x3000
	s_add_u32 s16, s16, 0x30000
	s_addc_u32 s17, s17, 0
	s_cmp_lg_u32 s16, 0x60000
	ds_read_b128 v[84:87], v32 offset:16384
	s_waitcnt vmcnt(15) lgkmcnt(4)
	v_pk_fma_f32 v[88:89], v[160:161], v[80:81], v[4:5] op_sel_hi:[1, 0, 1]
	v_pk_fma_f32 v[90:91], v[162:163], v[80:81], v[6:7] op_sel_hi:[1, 0, 1]
	ds_read_b128 v[4:7], v32 offset:4096
	s_waitcnt lgkmcnt(0)
	v_pk_fma_f32 v[92:93], v[160:161], v[4:5], v[16:17] op_sel_hi:[1, 0, 1]
	v_pk_fma_f32 v[94:95], v[162:163], v[4:5], v[18:19] op_sel_hi:[1, 0, 1]
	ds_read_b128 v[16:19], v32 offset:8192
	s_waitcnt lgkmcnt(0)
	v_pk_fma_f32 v[96:97], v[160:161], v[16:17], v[12:13] op_sel_hi:[1, 0, 1]
	v_pk_fma_f32 v[98:99], v[162:163], v[16:17], v[14:15] op_sel_hi:[1, 0, 1]
	ds_read_b128 v[12:15], v32 offset:12288
	s_waitcnt lgkmcnt(0)
	v_pk_fma_f32 v[8:9], v[160:161], v[12:13], v[8:9] op_sel_hi:[1, 0, 1]
	v_pk_fma_f32 v[76:77], v[160:161], v[84:85], v[0:1] op_sel_hi:[1, 0, 1]
	v_pk_fma_f32 v[10:11], v[162:163], v[12:13], v[10:11] op_sel_hi:[1, 0, 1]
	v_pk_fma_f32 v[78:79], v[162:163], v[84:85], v[2:3] op_sel_hi:[1, 0, 1]
	s_movk_i32 s0, 0x6000
	s_waitcnt vmcnt(14)
	v_pk_fma_f32 v[88:89], v[164:165], v[80:81], v[88:89] op_sel:[0, 1, 0]
	v_pk_fma_f32 v[80:81], v[166:167], v[80:81], v[90:91] op_sel:[0, 1, 0]
	v_pk_fma_f32 v[90:91], v[164:165], v[4:5], v[92:93] op_sel:[0, 1, 0]
	v_pk_fma_f32 v[92:93], v[164:165], v[16:17], v[96:97] op_sel:[0, 1, 0]
	v_pk_fma_f32 v[8:9], v[164:165], v[12:13], v[8:9] op_sel:[0, 1, 0]
	v_pk_fma_f32 v[10:11], v[166:167], v[12:13], v[10:11] op_sel:[0, 1, 0]
	v_pk_fma_f32 v[12:13], v[164:165], v[84:85], v[76:77] op_sel:[0, 1, 0]
	v_pk_fma_f32 v[4:5], v[166:167], v[4:5], v[94:95] op_sel:[0, 1, 0]
	v_pk_fma_f32 v[16:17], v[166:167], v[16:17], v[98:99] op_sel:[0, 1, 0]
	v_pk_fma_f32 v[76:77], v[166:167], v[84:85], v[78:79] op_sel:[0, 1, 0]
	s_mov_b32 s0, 0x9000
	s_waitcnt vmcnt(13)
	v_pk_fma_f32 v[78:79], v[168:169], v[82:83], v[88:89] op_sel_hi:[1, 0, 1]
	v_pk_fma_f32 v[84:85], v[168:169], v[6:7], v[90:91] op_sel_hi:[1, 0, 1]
	v_pk_fma_f32 v[88:89], v[168:169], v[18:19], v[92:93] op_sel_hi:[1, 0, 1]
	v_pk_fma_f32 v[8:9], v[168:169], v[14:15], v[8:9] op_sel_hi:[1, 0, 1]
	v_pk_fma_f32 v[12:13], v[168:169], v[86:87], v[12:13] op_sel_hi:[1, 0, 1]
	v_pk_fma_f32 v[80:81], v[170:171], v[82:83], v[80:81] op_sel_hi:[1, 0, 1]
	v_pk_fma_f32 v[4:5], v[170:171], v[6:7], v[4:5] op_sel_hi:[1, 0, 1]
	v_pk_fma_f32 v[90:91], v[170:171], v[18:19], v[16:17] op_sel_hi:[1, 0, 1]
	v_pk_fma_f32 v[10:11], v[170:171], v[14:15], v[10:11] op_sel_hi:[1, 0, 1]
	v_pk_fma_f32 v[76:77], v[170:171], v[86:87], v[76:77] op_sel_hi:[1, 0, 1]
	v_mov_b32_e32 v6, v83
	s_mov_b32 s0, 0xc000
	s_waitcnt vmcnt(12)
	v_pk_fma_f32 v[78:79], v[172:173], v[6:7], v[78:79] op_sel_hi:[1, 0, 1]
	v_pk_fma_f32 v[80:81], v[174:175], v[6:7], v[80:81] op_sel_hi:[1, 0, 1]
	v_mov_b32_e32 v6, v7
	v_pk_fma_f32 v[82:83], v[172:173], v[6:7], v[84:85] op_sel_hi:[1, 0, 1]
	v_pk_fma_f32 v[84:85], v[174:175], v[6:7], v[4:5] op_sel_hi:[1, 0, 1]
	v_mov_b32_e32 v4, v19
	v_pk_fma_f32 v[16:17], v[172:173], v[4:5], v[88:89] op_sel_hi:[1, 0, 1]
	v_pk_fma_f32 v[18:19], v[174:175], v[4:5], v[90:91] op_sel_hi:[1, 0, 1]
	v_mov_b32_e32 v4, v15
	v_mov_b32_e32 v6, v87
	v_pk_fma_f32 v[8:9], v[172:173], v[4:5], v[8:9] op_sel_hi:[1, 0, 1]
	v_pk_fma_f32 v[10:11], v[174:175], v[4:5], v[10:11] op_sel_hi:[1, 0, 1]
	v_pk_fma_f32 v[4:5], v[172:173], v[6:7], v[12:13] op_sel_hi:[1, 0, 1]
	v_pk_fma_f32 v[6:7], v[174:175], v[6:7], v[76:77] op_sel_hi:[1, 0, 1]
	s_mov_b32 s0, 0xf000
	s_waitcnt vmcnt(11)
	v_pk_fma_f32 v[12:13], v[176:177], v[28:29], v[78:79] op_sel_hi:[1, 0, 1]
	ds_read_b128 v[76:79], v32 offset:4112
	v_pk_fma_f32 v[14:15], v[178:179], v[28:29], v[80:81] op_sel_hi:[1, 0, 1]
	s_waitcnt lgkmcnt(0)
	v_pk_fma_f32 v[86:87], v[176:177], v[76:77], v[82:83] op_sel_hi:[1, 0, 1]
	ds_read_b128 v[80:83], v32 offset:8208
	v_pk_fma_f32 v[84:85], v[178:179], v[76:77], v[84:85] op_sel_hi:[1, 0, 1]
	s_waitcnt lgkmcnt(0)
	v_pk_fma_f32 v[88:89], v[176:177], v[80:81], v[16:17] op_sel_hi:[1, 0, 1]
	v_pk_fma_f32 v[90:91], v[178:179], v[80:81], v[18:19] op_sel_hi:[1, 0, 1]
	ds_read_b128 v[16:19], v32 offset:12304
	s_waitcnt lgkmcnt(0)
	v_pk_fma_f32 v[92:93], v[176:177], v[16:17], v[8:9] op_sel_hi:[1, 0, 1]
	v_pk_fma_f32 v[94:95], v[178:179], v[16:17], v[10:11] op_sel_hi:[1, 0, 1]
	ds_read_b128 v[8:11], v32 offset:16400
	s_waitcnt lgkmcnt(0)
	v_pk_fma_f32 v[4:5], v[176:177], v[8:9], v[4:5] op_sel_hi:[1, 0, 1]
	v_pk_fma_f32 v[6:7], v[178:179], v[8:9], v[6:7] op_sel_hi:[1, 0, 1]
	s_mov_b32 s0, 0x12000
	s_waitcnt vmcnt(10)
	v_pk_fma_f32 v[12:13], v[180:181], v[28:29], v[12:13] op_sel:[0, 1, 0]
	v_pk_fma_f32 v[14:15], v[182:183], v[28:29], v[14:15] op_sel:[0, 1, 0]
	v_pk_fma_f32 v[28:29], v[180:181], v[76:77], v[86:87] op_sel:[0, 1, 0]
	v_pk_fma_f32 v[76:77], v[182:183], v[76:77], v[84:85] op_sel:[0, 1, 0]
	v_pk_fma_f32 v[84:85], v[180:181], v[80:81], v[88:89] op_sel:[0, 1, 0]
	v_pk_fma_f32 v[86:87], v[180:181], v[16:17], v[92:93] op_sel:[0, 1, 0]
	v_pk_fma_f32 v[4:5], v[180:181], v[8:9], v[4:5] op_sel:[0, 1, 0]
	v_pk_fma_f32 v[80:81], v[182:183], v[80:81], v[90:91] op_sel:[0, 1, 0]
	v_pk_fma_f32 v[16:17], v[182:183], v[16:17], v[94:95] op_sel:[0, 1, 0]
	v_pk_fma_f32 v[6:7], v[182:183], v[8:9], v[6:7] op_sel:[0, 1, 0]
	s_mov_b32 s0, 0x15000
	s_waitcnt vmcnt(9)
	v_pk_fma_f32 v[8:9], v[184:185], v[30:31], v[12:13] op_sel_hi:[1, 0, 1]
	v_pk_fma_f32 v[12:13], v[186:187], v[30:31], v[14:15] op_sel_hi:[1, 0, 1]
	v_pk_fma_f32 v[14:15], v[184:185], v[78:79], v[28:29] op_sel_hi:[1, 0, 1]
	v_pk_fma_f32 v[28:29], v[186:187], v[78:79], v[76:77] op_sel_hi:[1, 0, 1]
	v_pk_fma_f32 v[76:77], v[184:185], v[82:83], v[84:85] op_sel_hi:[1, 0, 1]
	v_pk_fma_f32 v[84:85], v[184:185], v[18:19], v[86:87] op_sel_hi:[1, 0, 1]
	v_pk_fma_f32 v[4:5], v[184:185], v[10:11], v[4:5] op_sel_hi:[1, 0, 1]
	v_pk_fma_f32 v[80:81], v[186:187], v[82:83], v[80:81] op_sel_hi:[1, 0, 1]
	v_pk_fma_f32 v[16:17], v[186:187], v[18:19], v[16:17] op_sel_hi:[1, 0, 1]
	v_pk_fma_f32 v[6:7], v[186:187], v[10:11], v[6:7] op_sel_hi:[1, 0, 1]
	v_mov_b32_e32 v10, v31
	s_mov_b32 s0, 0x18000
	s_waitcnt vmcnt(8)
	v_pk_fma_f32 v[8:9], v[188:189], v[10:11], v[8:9] op_sel_hi:[1, 0, 1]
	v_pk_fma_f32 v[12:13], v[190:191], v[10:11], v[12:13] op_sel_hi:[1, 0, 1]
	v_mov_b32_e32 v10, v79
	v_pk_fma_f32 v[14:15], v[188:189], v[10:11], v[14:15] op_sel_hi:[1, 0, 1]
	v_pk_fma_f32 v[28:29], v[190:191], v[10:11], v[28:29] op_sel_hi:[1, 0, 1]
	v_mov_b32_e32 v10, v83
	v_pk_fma_f32 v[30:31], v[188:189], v[10:11], v[76:77] op_sel_hi:[1, 0, 1]
	v_pk_fma_f32 v[76:77], v[190:191], v[10:11], v[80:81] op_sel_hi:[1, 0, 1]
	v_mov_b32_e32 v10, v19
	v_pk_fma_f32 v[78:79], v[188:189], v[10:11], v[84:85] op_sel_hi:[1, 0, 1]
	v_pk_fma_f32 v[80:81], v[190:191], v[10:11], v[16:17] op_sel_hi:[1, 0, 1]
	v_mov_b32_e32 v10, v11
	v_pk_fma_f32 v[82:83], v[188:189], v[10:11], v[4:5] op_sel_hi:[1, 0, 1]
	v_pk_fma_f32 v[84:85], v[190:191], v[10:11], v[6:7] op_sel_hi:[1, 0, 1]
	ds_read_b128 v[0:3], v32 offset:4128
	ds_read_b128 v[4:7], v32 offset:8224
	s_mov_b32 s0, 0x1b000
	s_waitcnt vmcnt(7)
	v_pk_fma_f32 v[86:87], v[192:193], v[24:25], v[8:9] op_sel_hi:[1, 0, 1]
	v_pk_fma_f32 v[88:89], v[194:195], v[24:25], v[12:13] op_sel_hi:[1, 0, 1]
	s_waitcnt lgkmcnt(1)
	v_pk_fma_f32 v[90:91], v[192:193], v[0:1], v[14:15] op_sel_hi:[1, 0, 1]
	ds_read_b128 v[8:11], v32 offset:12320
	ds_read_b128 v[12:15], v32 offset:16416
	s_waitcnt lgkmcnt(2)
	v_pk_fma_f32 v[30:31], v[192:193], v[4:5], v[30:31] op_sel_hi:[1, 0, 1]
	v_pk_fma_f32 v[28:29], v[194:195], v[0:1], v[28:29] op_sel_hi:[1, 0, 1]
	v_pk_fma_f32 v[76:77], v[194:195], v[4:5], v[76:77] op_sel_hi:[1, 0, 1]
	s_waitcnt lgkmcnt(1)
	v_pk_fma_f32 v[78:79], v[192:193], v[8:9], v[78:79] op_sel_hi:[1, 0, 1]
	s_waitcnt lgkmcnt(0)
	v_pk_fma_f32 v[82:83], v[192:193], v[12:13], v[82:83] op_sel_hi:[1, 0, 1]
	v_pk_fma_f32 v[80:81], v[194:195], v[8:9], v[80:81] op_sel_hi:[1, 0, 1]
	v_pk_fma_f32 v[84:85], v[194:195], v[12:13], v[84:85] op_sel_hi:[1, 0, 1]
	s_mov_b32 s0, 0x1e000
	s_waitcnt vmcnt(6)
	v_pk_fma_f32 v[86:87], v[196:197], v[24:25], v[86:87] op_sel:[0, 1, 0]
	v_pk_fma_f32 v[24:25], v[198:199], v[24:25], v[88:89] op_sel:[0, 1, 0]
	v_pk_fma_f32 v[88:89], v[196:197], v[0:1], v[90:91] op_sel:[0, 1, 0]
	v_pk_fma_f32 v[0:1], v[198:199], v[0:1], v[28:29] op_sel:[0, 1, 0]
	v_pk_fma_f32 v[28:29], v[196:197], v[4:5], v[30:31] op_sel:[0, 1, 0]
	v_pk_fma_f32 v[4:5], v[198:199], v[4:5], v[76:77] op_sel:[0, 1, 0]
	v_pk_fma_f32 v[30:31], v[196:197], v[8:9], v[78:79] op_sel:[0, 1, 0]
	v_pk_fma_f32 v[76:77], v[196:197], v[12:13], v[82:83] op_sel:[0, 1, 0]
	v_pk_fma_f32 v[8:9], v[198:199], v[8:9], v[80:81] op_sel:[0, 1, 0]
	v_pk_fma_f32 v[12:13], v[198:199], v[12:13], v[84:85] op_sel:[0, 1, 0]
	s_mov_b32 s0, 0x21000
	s_waitcnt vmcnt(5)
	v_pk_fma_f32 v[78:79], v[200:201], v[26:27], v[86:87] op_sel_hi:[1, 0, 1]
	v_pk_fma_f32 v[86:87], v[202:203], v[10:11], v[8:9] op_sel_hi:[1, 0, 1]
	v_pk_fma_f32 v[82:83], v[200:201], v[6:7], v[28:29] op_sel_hi:[1, 0, 1]
	v_pk_fma_f32 v[84:85], v[200:201], v[10:11], v[30:31] op_sel_hi:[1, 0, 1]
	v_pk_fma_f32 v[24:25], v[202:203], v[26:27], v[24:25] op_sel_hi:[1, 0, 1]
	v_pk_fma_f32 v[80:81], v[200:201], v[2:3], v[88:89] op_sel_hi:[1, 0, 1]
	v_pk_fma_f32 v[0:1], v[202:203], v[2:3], v[0:1] op_sel_hi:[1, 0, 1]
	v_mov_b32_e32 v2, v27
	v_pk_fma_f32 v[4:5], v[202:203], v[6:7], v[4:5] op_sel_hi:[1, 0, 1]
	v_pk_fma_f32 v[76:77], v[200:201], v[14:15], v[76:77] op_sel_hi:[1, 0, 1]
	v_pk_fma_f32 v[12:13], v[202:203], v[14:15], v[12:13] op_sel_hi:[1, 0, 1]
	s_mov_b32 s0, 0x24000
	s_waitcnt vmcnt(4)
	v_pk_fma_f32 v[26:27], v[204:205], v[2:3], v[78:79] op_sel_hi:[1, 0, 1]
	v_pk_fma_f32 v[24:25], v[206:207], v[2:3], v[24:25] op_sel_hi:[1, 0, 1]
	v_mov_b32_e32 v2, v3
	v_pk_fma_f32 v[78:79], v[204:205], v[2:3], v[80:81] op_sel_hi:[1, 0, 1]
	v_pk_fma_f32 v[80:81], v[206:207], v[2:3], v[0:1] op_sel_hi:[1, 0, 1]
	v_mov_b32_e32 v0, v7
	v_pk_fma_f32 v[16:17], v[204:205], v[0:1], v[82:83] op_sel_hi:[1, 0, 1]
	v_pk_fma_f32 v[18:19], v[206:207], v[0:1], v[4:5] op_sel_hi:[1, 0, 1]
	v_mov_b32_e32 v0, v11
	v_pk_fma_f32 v[8:9], v[204:205], v[0:1], v[84:85] op_sel_hi:[1, 0, 1]
	v_pk_fma_f32 v[10:11], v[206:207], v[0:1], v[86:87] op_sel_hi:[1, 0, 1]
	v_mov_b32_e32 v0, v15
	v_pk_fma_f32 v[4:5], v[204:205], v[0:1], v[76:77] op_sel_hi:[1, 0, 1]
	v_pk_fma_f32 v[6:7], v[206:207], v[0:1], v[12:13] op_sel_hi:[1, 0, 1]
	ds_read_b128 v[28:31], v32 offset:8240
	s_waitcnt vmcnt(3)
	v_pk_fma_f32 v[12:13], v[208:209], v[20:21], v[26:27] op_sel_hi:[1, 0, 1]
	v_pk_fma_f32 v[14:15], v[210:211], v[20:21], v[24:25] op_sel_hi:[1, 0, 1]
	ds_read_b128 v[24:27], v32 offset:4144
	s_waitcnt lgkmcnt(1)
	v_pk_fma_f32 v[16:17], v[208:209], v[28:29], v[16:17] op_sel_hi:[1, 0, 1]
	v_pk_fma_f32 v[18:19], v[210:211], v[28:29], v[18:19] op_sel_hi:[1, 0, 1]
	s_waitcnt lgkmcnt(0)
	v_pk_fma_f32 v[84:85], v[208:209], v[24:25], v[78:79] op_sel_hi:[1, 0, 1]
	v_pk_fma_f32 v[86:87], v[210:211], v[24:25], v[80:81] op_sel_hi:[1, 0, 1]
	ds_read_b128 v[76:79], v32 offset:12336
	ds_read_b128 v[80:83], v32 offset:16432
	v_add_u32_e32 v32, 64, v32
	s_waitcnt lgkmcnt(1)
	v_pk_fma_f32 v[8:9], v[208:209], v[76:77], v[8:9] op_sel_hi:[1, 0, 1]
	s_waitcnt lgkmcnt(0)
	v_pk_fma_f32 v[4:5], v[208:209], v[80:81], v[4:5] op_sel_hi:[1, 0, 1]
	v_pk_fma_f32 v[10:11], v[210:211], v[76:77], v[10:11] op_sel_hi:[1, 0, 1]
	v_pk_fma_f32 v[6:7], v[210:211], v[80:81], v[6:7] op_sel_hi:[1, 0, 1]
	s_waitcnt vmcnt(2)
	v_pk_fma_f32 v[12:13], v[212:213], v[20:21], v[12:13] op_sel:[0, 1, 0]
	v_pk_fma_f32 v[14:15], v[214:215], v[20:21], v[14:15] op_sel:[0, 1, 0]
	v_pk_fma_f32 v[20:21], v[212:213], v[24:25], v[84:85] op_sel:[0, 1, 0]
	v_pk_fma_f32 v[16:17], v[212:213], v[28:29], v[16:17] op_sel:[0, 1, 0]
	v_pk_fma_f32 v[8:9], v[212:213], v[76:77], v[8:9] op_sel:[0, 1, 0]
	v_pk_fma_f32 v[4:5], v[212:213], v[80:81], v[4:5] op_sel:[0, 1, 0]
	v_pk_fma_f32 v[24:25], v[214:215], v[24:25], v[86:87] op_sel:[0, 1, 0]
	v_pk_fma_f32 v[18:19], v[214:215], v[28:29], v[18:19] op_sel:[0, 1, 0]
	v_pk_fma_f32 v[10:11], v[214:215], v[76:77], v[10:11] op_sel:[0, 1, 0]
	v_pk_fma_f32 v[6:7], v[214:215], v[80:81], v[6:7] op_sel:[0, 1, 0]
	s_waitcnt vmcnt(1)
	v_pk_fma_f32 v[12:13], v[216:217], v[22:23], v[12:13] op_sel_hi:[1, 0, 1]
	v_pk_fma_f32 v[20:21], v[216:217], v[26:27], v[20:21] op_sel_hi:[1, 0, 1]
	v_pk_fma_f32 v[28:29], v[216:217], v[30:31], v[16:17] op_sel_hi:[1, 0, 1]
	v_pk_fma_f32 v[8:9], v[216:217], v[78:79], v[8:9] op_sel_hi:[1, 0, 1]
	v_pk_fma_f32 v[80:81], v[216:217], v[82:83], v[4:5] op_sel_hi:[1, 0, 1]
	v_pk_fma_f32 v[14:15], v[218:219], v[22:23], v[14:15] op_sel_hi:[1, 0, 1]
	v_pk_fma_f32 v[24:25], v[218:219], v[26:27], v[24:25] op_sel_hi:[1, 0, 1]
	v_pk_fma_f32 v[76:77], v[218:219], v[30:31], v[18:19] op_sel_hi:[1, 0, 1]
	v_pk_fma_f32 v[10:11], v[218:219], v[78:79], v[10:11] op_sel_hi:[1, 0, 1]
	v_pk_fma_f32 v[84:85], v[218:219], v[82:83], v[6:7] op_sel_hi:[1, 0, 1]
	v_mov_b32_e32 v6, v23
	s_waitcnt vmcnt(0)
	v_pk_fma_f32 v[4:5], v[220:221], v[6:7], v[12:13] op_sel_hi:[1, 0, 1]
	v_mov_b32_e32 v12, v27
	v_pk_fma_f32 v[16:17], v[220:221], v[12:13], v[20:21] op_sel_hi:[1, 0, 1]
	v_mov_b32_e32 v20, v79
	v_pk_fma_f32 v[6:7], v[222:223], v[6:7], v[14:15] op_sel_hi:[1, 0, 1]
	v_mov_b32_e32 v14, v31
	v_pk_fma_f32 v[8:9], v[220:221], v[20:21], v[8:9] op_sel_hi:[1, 0, 1]
	v_pk_fma_f32 v[10:11], v[222:223], v[20:21], v[10:11] op_sel_hi:[1, 0, 1]
	v_mov_b32_e32 v20, v83
	v_pk_fma_f32 v[18:19], v[222:223], v[12:13], v[24:25] op_sel_hi:[1, 0, 1]
	v_pk_fma_f32 v[12:13], v[220:221], v[14:15], v[28:29] op_sel_hi:[1, 0, 1]
	v_pk_fma_f32 v[14:15], v[222:223], v[14:15], v[76:77] op_sel_hi:[1, 0, 1]
	v_pk_fma_f32 v[0:1], v[220:221], v[20:21], v[80:81] op_sel_hi:[1, 0, 1]
	v_pk_fma_f32 v[2:3], v[222:223], v[20:21], v[84:85] op_sel_hi:[1, 0, 1]
	s_cbranch_scc1 .LBB0_141
	ds_write_b128 v66, v[4:7] offset:20480
	ds_write_b128 v66, v[16:19] offset:20608
	ds_write_b128 v66, v[12:15] offset:20736
	ds_write_b128 v66, v[8:11] offset:20864
	ds_write_b128 v66, v[0:3] offset:20992
	s_waitcnt lgkmcnt(0)
	s_barrier
	s_and_saveexec_b64 s[16:17], s[4:5]
	s_cbranch_execz .LBB0_20
	v_or_b32_e32 v0, s18, v52
	v_ashrrev_i32_e32 v1, 31, v0
	v_lshl_add_u64 v[0:1], v[0:1], 2, s[14:15]
	global_load_dword v32, v[0:1], off
	v_add_u32_e32 v2, 0x5000, v67
	v_add_u32_e32 v4, 0x5400, v67
	v_add_u32_e32 v6, 0x5a00, v67
	v_add_u32_e32 v8, 0x5e00, v67
	v_add_u32_e32 v10, 0x6400, v67
	v_add_u32_e32 v12, 0x6800, v67
	v_add_u32_e32 v14, 0x6e00, v67
	v_add_u32_e32 v16, 0x7200, v67
	v_add_u32_e32 v18, 0x7800, v67
	v_add_u32_e32 v20, 0x7c00, v67
	v_add_u32_e32 v22, 0x8200, v67
	v_add_u32_e32 v24, 0x8600, v67
	v_add_u32_e32 v26, 0x8c00, v67
	v_add_u32_e32 v28, 0x9000, v67
	v_add_u32_e32 v30, 0x9600, v67
	v_add_u32_e32 v34, 0x9a00, v67
	ds_read2_b32 v[2:3], v2 offset1:160
	ds_read2_b32 v[4:5], v4 offset0:64 offset1:224
	ds_read2_b32 v[6:7], v6 offset1:160
	ds_read2_b32 v[8:9], v8 offset0:64 offset1:224
	ds_read2_b32 v[10:11], v10 offset1:160
	ds_read2_b32 v[12:13], v12 offset0:64 offset1:224
	ds_read2_b32 v[14:15], v14 offset1:160
	ds_read2_b32 v[16:17], v16 offset0:64 offset1:224
	ds_read2_b32 v[18:19], v18 offset1:160
	ds_read2_b32 v[20:21], v20 offset0:64 offset1:224
	ds_read2_b32 v[22:23], v22 offset1:160
	ds_read2_b32 v[24:25], v24 offset0:64 offset1:224
	ds_read2_b32 v[26:27], v26 offset1:160
	ds_read2_b32 v[28:29], v28 offset0:64 offset1:224
	ds_read2_b32 v[30:31], v30 offset1:160
	ds_read2_b32 v[48:49], v34 offset0:64 offset1:224
	s_waitcnt lgkmcnt(14)
	v_add_f32_e32 v2, 0, v2
	v_add_f32_e32 v2, v2, v3
	v_add_f32_e32 v2, v2, v4
	v_add_f32_e32 v2, v2, v5
	s_waitcnt lgkmcnt(13)
	v_add_f32_e32 v2, v2, v6
	v_add_f32_e32 v2, v2, v7
	s_waitcnt lgkmcnt(12)
	v_add_f32_e32 v2, v2, v8
	v_add_f32_e32 v2, v2, v9
	s_waitcnt lgkmcnt(11)
	v_add_f32_e32 v2, v2, v10
	v_add_f32_e32 v2, v2, v11
	s_waitcnt lgkmcnt(10)
	v_add_f32_e32 v2, v2, v12
	v_add_f32_e32 v2, v2, v13
	s_waitcnt lgkmcnt(9)
	v_add_f32_e32 v2, v2, v14
	v_add_f32_e32 v2, v2, v15
	s_waitcnt lgkmcnt(8)
	v_add_f32_e32 v2, v2, v16
	v_add_f32_e32 v2, v2, v17
	s_waitcnt lgkmcnt(7)
	v_add_f32_e32 v2, v2, v18
	v_add_f32_e32 v2, v2, v19
	s_waitcnt lgkmcnt(6)
	v_add_f32_e32 v2, v2, v20
	v_add_f32_e32 v2, v2, v21
	s_waitcnt lgkmcnt(5)
	v_add_f32_e32 v2, v2, v22
	v_add_f32_e32 v2, v2, v23
	s_waitcnt lgkmcnt(4)
	v_add_f32_e32 v2, v2, v24
	v_add_f32_e32 v2, v2, v25
	s_waitcnt lgkmcnt(3)
	v_add_f32_e32 v2, v2, v26
	v_add_f32_e32 v2, v2, v27
	s_waitcnt lgkmcnt(2)
	v_add_f32_e32 v2, v2, v28
	v_mad_u64_u32 v[0:1], s[0:1], s37, 5, v[40:41]
	v_add_f32_e32 v2, v2, v29
	v_mul_lo_u32 v0, v0, s96
	s_waitcnt lgkmcnt(1)
	v_add_f32_e32 v2, v2, v30
	v_add_u32_e32 v0, s18, v0
	v_add_f32_e32 v2, v2, v31
	v_or_b32_e32 v0, v0, v52
	s_waitcnt lgkmcnt(0)
	v_add_f32_e32 v2, v2, v48
	v_ashrrev_i32_e32 v1, 31, v0
	v_add_f32_e32 v2, v2, v49
	v_lshl_add_u64 v[0:1], v[0:1], 2, s[52:53]
	s_waitcnt vmcnt(0)
	v_add_f32_e32 v2, v2, v32
	global_store_dword v[0:1], v2, off
	s_branch .LBB0_20
